# stack + hyena even-loop load batching (branch via existing long-branch trampoline) + barrier XGEN-before-inv
# speedup vs baseline: 1.0020x; 1.0020x over previous
.Ltramp1445:
	s_getpc_b64 s[98:99]
